# v021 + rope-table loads of the layer-A in-projection epilogues (phases 1 and 18) software-pipelined one iteration ahead
# baseline (speedup 1.0000x reference)
; __device__ __forceinline__ u32x4 pack8(const f32x4 a, const f32x4 b) { u32x4 w; w.x = cvt_pk_bf16(a[0], a[1]); w.y = cvt_pk_bf16(a[2], a[3]); w.z = cvt_pk_bf16(b[0], b[1]); w.w = cvt_pk_bf16(b[2], b[3]); return w; }
; __device__ __forceinline__ void rope8(const float* tab64, int row, int fq, const f32x4 x1a, const f32x4 x2a, const f32x4 x1b, const f32x4 x2b, f32x4& a1, f32x4& a2, f32x4& b1, f32x4& b2) {
;     const float* tp = tab64 + ((size_t)pos_index_(row) * 32 + 8 * fq) * 2;
;     const f32x4 c0 = *(const f32x4*)tp, c1 = *(const f32x4*)(tp + 4), c2 = *(const f32x4*)(tp + 8), c3 = *(const f32x4*)(tp + 12);
;     rope4(x1a, x2a, c0, c1, a1, a2); rope4(x1b, x2b, c2, c3, b1, b2);
;     __device__ __forceinline__ void operator()(const f32x4 (&acc)[2][2][4][2], const Unit& u, int wr, int wc, int fr, int fq) const {
;     ...
;             for (int m = 0; m < 4; ++m) {
;                 const int rowb = u.pm * BM + ai * HALF + wr * 64 + m * 16, row0 = rowb + (fr & 7); const size_t ro0 = (size_t)row0 * 2048;
;                 float* f0 = row0 < 8192 ? (type == 1 ? okp : ovp) + ro0 : (type == 1 ? oks : ovs) + (ro0 - (size_t)8192 * 2048);
;                 if (type < 2) {
;                     f32x4 a1, a2, b1, b2; rope8(tab64, rowb + fr, fq, acc[ai][0][m][0], acc[ai][1][m][0], acc[ai][0][m][1], acc[ai][1][m][1], a1, a2, b1, b2);
;                     if (type == 0) { a1 = a1 * qscale; a2 = a2 * qscale; b1 = b1 * qscale; b2 = b2 * qscale; }
;                     st2_bf16((type == 0 ? QA : KA) + ro0 + cw + (lo ? 0 : 32), 8 * 2048, pack8(a1, b1), pack8(a2, b2), lo, dry);
;                     if (type == 1) { st2_f32<true>(f0 + cw + (lo ? 0 : 4), 8 * 2048, a1, b1, lo, dry); st2_f32<true>(f0 + cw + 32 + (lo ? 0 : 4), 8 * 2048, a2, b2, lo, dry); }
.LBB0_192:
	v_cndmask_b32_e64 v130, 0, 1, s[6:7]
	s_andn2_b64 vcc, exec, s[10:11]
	v_lshlrev_b32_e32 v168, 2, v154
	v_cmp_ne_u32_e64 s[6:7], 1, v130
	s_cbranch_vccnz .LBB0_197
	v_or_b32_e32 v130, s31, v141
	v_bitop3_b32 v131, s31, v161, v141 bitop3:0xc8
	v_cmp_gt_i32_e32 vcc, s49, v130
	v_readlane_b32 s10, v254, 22
	v_readlane_b32 s11, v254, 23
	v_cndmask_b32_e32 v130, v155, v131, vcc
	v_lshl_or_b32 v130, v130, 8, v168
	s_nop 2
	global_load_dwordx4 v[170:173], v130, s[10:11]
	global_load_dwordx4 v[174:177], v130, s[10:11] offset:16
	global_load_dwordx4 v[178:181], v130, s[10:11] offset:32
	global_load_dwordx4 v[182:185], v130, s[10:11] offset:48
	v_readlane_b32 s100, v254, 22
	v_readlane_b32 s101, v254, 23
	s_add_i32 s98, s35, s66
	v_or_b32_e32 v252, s98, v141
	v_bitop3_b32 v253, s98, v162, v141 bitop3:0xc8
	v_and_or_b32 v236, v252, 31, v163
	v_cmp_gt_i32_e32 vcc, s49, v252
	v_cndmask_b32_e32 v252, v236, v253, vcc
	v_lshl_or_b32 v252, v252, 8, v168
	s_nop 2
	global_load_dwordx4 v[236:239], v252, s[100:101]
	global_load_dwordx4 v[240:243], v252, s[100:101] offset:16
	global_load_dwordx4 v[244:247], v252, s[100:101] offset:32
	global_load_dwordx4 v[248:251], v252, s[100:101] offset:48
	s_load_dwordx4 s[72:75], s[88:89], 0xe8
	s_and_b64 vcc, exec, s[6:7]
	s_mov_b64 s[10:11], 0x1b500000
	s_waitcnt vmcnt(4)
	v_mov_b32_e32 v130, v170
	v_mul_f32_e32 v170, v128, v174
	v_mul_f32_e32 v186, v120, v175
	v_mul_f32_e32 v174, v120, v174
	v_mul_f32_e32 v188, v128, v175
	v_mov_b32_e32 v120, v129
	v_mov_b32_e32 v128, v121
	v_mov_b32_e32 v190, v178
	v_mul_f32_e32 v178, v124, v182
	v_mul_f32_e32 v192, v116, v183
	v_mul_f32_e32 v182, v116, v182
	v_mul_f32_e32 v194, v124, v183
	v_mov_b32_e32 v116, v125
	v_mov_b32_e32 v124, v117
	v_mov_b32_e32 v131, v172
	v_mov_b32_e32 v172, v171
	v_mov_b32_e32 v191, v180
	v_mov_b32_e32 v180, v179
	v_pk_mul_f32 v[120:121], v[120:121], v[176:177]
	v_pk_mul_f32 v[128:129], v[128:129], v[176:177]
	v_pk_mul_f32 v[198:199], v[116:117], v[184:185]
	v_pk_mul_f32 v[184:185], v[124:125], v[184:185]
	v_pk_mul_f32 v[196:197], v[118:119], v[172:173]
	v_pk_mul_f32 v[172:173], v[126:127], v[172:173]
	v_pk_mul_f32 v[176:177], v[114:115], v[180:181]
	v_pk_mul_f32 v[180:181], v[122:123], v[180:181]
	v_mov_b32_e32 v171, v120
	v_mov_b32_e32 v187, v121
	v_mov_b32_e32 v175, v128
	v_mov_b32_e32 v189, v129
	v_mov_b32_e32 v179, v198
	v_mov_b32_e32 v193, v199
	v_mov_b32_e32 v183, v184
	v_mov_b32_e32 v195, v185
	v_pk_fma_f32 v[124:125], v[126:127], v[130:131], v[196:197] neg_lo:[0,0,1] neg_hi:[0,0,1]
	v_pk_fma_f32 v[116:117], v[118:119], v[130:131], v[172:173]
	v_pk_fma_f32 v[128:129], v[122:123], v[190:191], v[176:177] neg_lo:[0,0,1] neg_hi:[0,0,1]
	v_pk_fma_f32 v[120:121], v[114:115], v[190:191], v[180:181]
	v_pk_add_f32 v[126:127], v[170:171], v[186:187] neg_lo:[0,1] neg_hi:[0,1]
	v_pk_add_f32 v[118:119], v[174:175], v[188:189]
	v_pk_add_f32 v[130:131], v[178:179], v[192:193] neg_lo:[0,1] neg_hi:[0,1]
	v_pk_add_f32 v[122:123], v[182:183], v[194:195]
	s_cbranch_vccnz .LBB0_195
	v_pk_mul_f32 v[126:127], v[126:127], s[28:29] op_sel_hi:[1,0]
	v_pk_mul_f32 v[124:125], v[124:125], s[28:29] op_sel_hi:[1,0]
	v_pk_mul_f32 v[118:119], v[118:119], s[28:29] op_sel_hi:[1,0]
	v_pk_mul_f32 v[116:117], v[116:117], s[28:29] op_sel_hi:[1,0]
	v_pk_mul_f32 v[130:131], v[130:131], s[28:29] op_sel_hi:[1,0]
	v_pk_mul_f32 v[128:129], v[128:129], s[28:29] op_sel_hi:[1,0]
	v_pk_mul_f32 v[122:123], v[122:123], s[28:29] op_sel_hi:[1,0]
	v_pk_mul_f32 v[120:121], v[120:121], s[28:29] op_sel_hi:[1,0]
	s_mov_b64 s[10:11], 0x19300000

; __device__ __forceinline__ u32x4 pack8(const f32x4 a, const f32x4 b) { u32x4 w; w.x = cvt_pk_bf16(a[0], a[1]); w.y = cvt_pk_bf16(a[2], a[3]); w.z = cvt_pk_bf16(b[0], b[1]); w.w = cvt_pk_bf16(b[2], b[3]); return w; }
; __device__ __forceinline__ void rope8(const float* tab64, int row, int fq, const f32x4 x1a, const f32x4 x2a, const f32x4 x1b, const f32x4 x2b, f32x4& a1, f32x4& a2, f32x4& b1, f32x4& b2) {
;     const float* tp = tab64 + ((size_t)pos_index_(row) * 32 + 8 * fq) * 2;
;     const f32x4 c0 = *(const f32x4*)tp, c1 = *(const f32x4*)(tp + 4), c2 = *(const f32x4*)(tp + 8), c3 = *(const f32x4*)(tp + 12);
;     rope4(x1a, x2a, c0, c1, a1, a2); rope4(x1b, x2b, c2, c3, b1, b2);
;     __device__ __forceinline__ void operator()(const f32x4 (&acc)[2][2][4][2], const Unit& u, int wr, int wc, int fr, int fq) const {
;     ...
;             for (int m = 0; m < 4; ++m) {
;                 const int rowb = u.pm * BM + ai * HALF + wr * 64 + m * 16, row0 = rowb + (fr & 7); const size_t ro0 = (size_t)row0 * 2048;
;                 float* f0 = row0 < 8192 ? (type == 1 ? okp : ovp) + ro0 : (type == 1 ? oks : ovs) + (ro0 - (size_t)8192 * 2048);
;                 if (type < 2) {
;                     f32x4 a1, a2, b1, b2; rope8(tab64, rowb + fr, fq, acc[ai][0][m][0], acc[ai][1][m][0], acc[ai][0][m][1], acc[ai][1][m][1], a1, a2, b1, b2);
;                     if (type == 0) { a1 = a1 * qscale; a2 = a2 * qscale; b1 = b1 * qscale; b2 = b2 * qscale; }
;                     st2_bf16((type == 0 ? QA : KA) + ro0 + cw + (lo ? 0 : 32), 8 * 2048, pack8(a1, b1), pack8(a2, b2), lo, dry);
;                     if (type == 1) { st2_f32<true>(f0 + cw + (lo ? 0 : 4), 8 * 2048, a1, b1, lo, dry); st2_f32<true>(f0 + cw + 32 + (lo ? 0 : 4), 8 * 2048, a2, b2, lo, dry); }
.LBB0_207:
	s_andn2_b64 vcc, exec, s[42:43]
	s_cbranch_vccnz .LBB0_212
	s_andn2_b64 vcc, exec, s[0:1]
	s_cbranch_vccnz .Lrope_q_p1_1
	s_waitcnt vmcnt(6)
	s_branch .Lrope_j_p1_1

; __device__ __forceinline__ u32x4 pack8(const f32x4 a, const f32x4 b) { u32x4 w; w.x = cvt_pk_bf16(a[0], a[1]); w.y = cvt_pk_bf16(a[2], a[3]); w.z = cvt_pk_bf16(b[0], b[1]); w.w = cvt_pk_bf16(b[2], b[3]); return w; }
; __device__ __forceinline__ void rope8(const float* tab64, int row, int fq, const f32x4 x1a, const f32x4 x2a, const f32x4 x1b, const f32x4 x2b, f32x4& a1, f32x4& a2, f32x4& b1, f32x4& b2) {
;     const float* tp = tab64 + ((size_t)pos_index_(row) * 32 + 8 * fq) * 2;
;     const f32x4 c0 = *(const f32x4*)tp, c1 = *(const f32x4*)(tp + 4), c2 = *(const f32x4*)(tp + 8), c3 = *(const f32x4*)(tp + 12);
;     rope4(x1a, x2a, c0, c1, a1, a2); rope4(x1b, x2b, c2, c3, b1, b2);
;     __device__ __forceinline__ void operator()(const f32x4 (&acc)[2][2][4][2], const Unit& u, int wr, int wc, int fr, int fq) const {
;     ...
;             for (int m = 0; m < 4; ++m) {
;                 const int rowb = u.pm * BM + ai * HALF + wr * 64 + m * 16, row0 = rowb + (fr & 7); const size_t ro0 = (size_t)row0 * 2048;
;                 float* f0 = row0 < 8192 ? (type == 1 ? okp : ovp) + ro0 : (type == 1 ? oks : ovs) + (ro0 - (size_t)8192 * 2048);
;                 if (type < 2) {
;                     f32x4 a1, a2, b1, b2; rope8(tab64, rowb + fr, fq, acc[ai][0][m][0], acc[ai][1][m][0], acc[ai][0][m][1], acc[ai][1][m][1], a1, a2, b1, b2);
;                     if (type == 0) { a1 = a1 * qscale; a2 = a2 * qscale; b1 = b1 * qscale; b2 = b2 * qscale; }
;                     st2_bf16((type == 0 ? QA : KA) + ro0 + cw + (lo ? 0 : 32), 8 * 2048, pack8(a1, b1), pack8(a2, b2), lo, dry);
;                     if (type == 1) { st2_f32<true>(f0 + cw + (lo ? 0 : 4), 8 * 2048, a1, b1, lo, dry); st2_f32<true>(f0 + cw + 32 + (lo ? 0 : 4), 8 * 2048, a2, b2, lo, dry); }
.Lrope_j_p1_1:
	v_mov_b64_e32 v[120:121], v[236:237]
	v_mov_b64_e32 v[122:123], v[238:239]
	v_mov_b64_e32 v[124:125], v[240:241]
	v_mov_b64_e32 v[126:127], v[242:243]
	v_mov_b64_e32 v[128:129], v[244:245]
	v_mov_b64_e32 v[130:131], v[246:247]
	v_mov_b64_e32 v[150:151], v[248:249]
	v_mov_b64_e32 v[152:153], v[250:251]
	v_readlane_b32 s100, v254, 22
	v_readlane_b32 s101, v254, 23
	s_add_i32 s98, s35, s67
	v_or_b32_e32 v252, s98, v141
	v_bitop3_b32 v253, s98, v165, v141 bitop3:0xc8
	v_and_or_b32 v236, v252, 47, v163
	v_cmp_gt_i32_e32 vcc, s49, v252
	v_cndmask_b32_e32 v252, v236, v253, vcc
	v_lshl_or_b32 v252, v252, 8, v168
	s_nop 2
	global_load_dwordx4 v[236:239], v252, s[100:101]
	global_load_dwordx4 v[240:243], v252, s[100:101] offset:16
	global_load_dwordx4 v[244:247], v252, s[100:101] offset:32
	global_load_dwordx4 v[248:251], v252, s[100:101] offset:48
	s_and_b64 vcc, exec, s[6:7]
	s_mov_b64 s[40:41], 0x1b500000
	v_mov_b32_e32 v114, v120
	v_mul_f32_e32 v120, v112, v124
	v_mul_f32_e32 v170, v104, v125
	v_mul_f32_e32 v124, v104, v124
	v_mul_f32_e32 v172, v112, v125
	v_mov_b32_e32 v104, v113
	v_mov_b32_e32 v112, v105
	v_mov_b32_e32 v174, v128
	v_mul_f32_e32 v128, v108, v150
	v_mul_f32_e32 v176, v100, v151
	v_mul_f32_e32 v150, v100, v150
	v_mul_f32_e32 v178, v108, v151
	v_mov_b32_e32 v100, v109
	v_mov_b32_e32 v108, v101
	v_mov_b32_e32 v115, v122
	v_mov_b32_e32 v122, v121
	v_mov_b32_e32 v175, v130
	v_mov_b32_e32 v130, v129
	v_pk_mul_f32 v[104:105], v[104:105], v[126:127]
	v_pk_mul_f32 v[112:113], v[112:113], v[126:127]
	v_pk_mul_f32 v[182:183], v[100:101], v[152:153]
	v_pk_mul_f32 v[152:153], v[108:109], v[152:153]
	v_pk_mul_f32 v[180:181], v[102:103], v[122:123]
	v_pk_mul_f32 v[122:123], v[110:111], v[122:123]
	v_pk_mul_f32 v[126:127], v[98:99], v[130:131]
	v_pk_mul_f32 v[130:131], v[106:107], v[130:131]
	v_mov_b32_e32 v121, v104
	v_mov_b32_e32 v171, v105
	v_mov_b32_e32 v125, v112
	v_mov_b32_e32 v173, v113
	v_mov_b32_e32 v129, v182
	v_mov_b32_e32 v177, v183
	v_mov_b32_e32 v151, v152
	v_mov_b32_e32 v179, v153
	v_pk_fma_f32 v[108:109], v[110:111], v[114:115], v[180:181] neg_lo:[0,0,1] neg_hi:[0,0,1]
	v_pk_fma_f32 v[100:101], v[102:103], v[114:115], v[122:123]
	v_pk_fma_f32 v[112:113], v[106:107], v[174:175], v[126:127] neg_lo:[0,0,1] neg_hi:[0,0,1]
	v_pk_fma_f32 v[104:105], v[98:99], v[174:175], v[130:131]
	v_pk_add_f32 v[110:111], v[120:121], v[170:171] neg_lo:[0,1] neg_hi:[0,1]
	v_pk_add_f32 v[102:103], v[124:125], v[172:173]
	v_pk_add_f32 v[114:115], v[128:129], v[176:177] neg_lo:[0,1] neg_hi:[0,1]
	v_pk_add_f32 v[106:107], v[150:151], v[178:179]
	s_cbranch_vccnz .LBB0_210
	v_pk_mul_f32 v[110:111], v[110:111], s[28:29] op_sel_hi:[1,0]
	v_pk_mul_f32 v[108:109], v[108:109], s[28:29] op_sel_hi:[1,0]
	v_pk_mul_f32 v[102:103], v[102:103], s[28:29] op_sel_hi:[1,0]
	v_pk_mul_f32 v[100:101], v[100:101], s[28:29] op_sel_hi:[1,0]
	v_pk_mul_f32 v[114:115], v[114:115], s[28:29] op_sel_hi:[1,0]
	v_pk_mul_f32 v[112:113], v[112:113], s[28:29] op_sel_hi:[1,0]
	v_pk_mul_f32 v[106:107], v[106:107], s[28:29] op_sel_hi:[1,0]
	v_pk_mul_f32 v[104:105], v[104:105], s[28:29] op_sel_hi:[1,0]
	s_mov_b64 s[40:41], 0x19300000

; __device__ __forceinline__ u32x4 pack8(const f32x4 a, const f32x4 b) { u32x4 w; w.x = cvt_pk_bf16(a[0], a[1]); w.y = cvt_pk_bf16(a[2], a[3]); w.z = cvt_pk_bf16(b[0], b[1]); w.w = cvt_pk_bf16(b[2], b[3]); return w; }
; __device__ __forceinline__ void rope8(const float* tab64, int row, int fq, const f32x4 x1a, const f32x4 x2a, const f32x4 x1b, const f32x4 x2b, f32x4& a1, f32x4& a2, f32x4& b1, f32x4& b2) {
;     const float* tp = tab64 + ((size_t)pos_index_(row) * 32 + 8 * fq) * 2;
;     const f32x4 c0 = *(const f32x4*)tp, c1 = *(const f32x4*)(tp + 4), c2 = *(const f32x4*)(tp + 8), c3 = *(const f32x4*)(tp + 12);
;     rope4(x1a, x2a, c0, c1, a1, a2); rope4(x1b, x2b, c2, c3, b1, b2);
;     __device__ __forceinline__ void operator()(const f32x4 (&acc)[2][2][4][2], const Unit& u, int wr, int wc, int fr, int fq) const {
;     ...
;             for (int m = 0; m < 4; ++m) {
;                 const int rowb = u.pm * BM + ai * HALF + wr * 64 + m * 16, row0 = rowb + (fr & 7); const size_t ro0 = (size_t)row0 * 2048;
;                 float* f0 = row0 < 8192 ? (type == 1 ? okp : ovp) + ro0 : (type == 1 ? oks : ovs) + (ro0 - (size_t)8192 * 2048);
;                 if (type < 2) {
;                     f32x4 a1, a2, b1, b2; rope8(tab64, rowb + fr, fq, acc[ai][0][m][0], acc[ai][1][m][0], acc[ai][0][m][1], acc[ai][1][m][1], a1, a2, b1, b2);
;                     if (type == 0) { a1 = a1 * qscale; a2 = a2 * qscale; b1 = b1 * qscale; b2 = b2 * qscale; }
;                     st2_bf16((type == 0 ? QA : KA) + ro0 + cw + (lo ? 0 : 32), 8 * 2048, pack8(a1, b1), pack8(a2, b2), lo, dry);
;                     if (type == 1) { st2_f32<true>(f0 + cw + (lo ? 0 : 4), 8 * 2048, a1, b1, lo, dry); st2_f32<true>(f0 + cw + 32 + (lo ? 0 : 4), 8 * 2048, a2, b2, lo, dry); }
.Lrope_j_p1_2:
	v_mov_b64_e32 v[104:105], v[236:237]
	v_mov_b64_e32 v[106:107], v[238:239]
	v_mov_b64_e32 v[108:109], v[240:241]
	v_mov_b64_e32 v[110:111], v[242:243]
	v_mov_b64_e32 v[112:113], v[244:245]
	v_mov_b64_e32 v[114:115], v[246:247]
	v_mov_b64_e32 v[116:117], v[248:249]
	v_mov_b64_e32 v[118:119], v[250:251]
	v_readlane_b32 s100, v254, 22
	v_readlane_b32 s101, v254, 23
	s_add_i32 s98, s35, s68
	v_or_b32_e32 v252, s98, v141
	v_bitop3_b32 v253, s98, v166, v141 bitop3:0xc8
	v_and_or_b32 v236, v252, 63, v163
	v_cmp_gt_i32_e32 vcc, s49, v252
	v_cndmask_b32_e32 v252, v236, v253, vcc
	v_lshl_or_b32 v252, v252, 8, v168
	s_nop 2
	global_load_dwordx4 v[236:239], v252, s[100:101]
	global_load_dwordx4 v[240:243], v252, s[100:101] offset:16
	global_load_dwordx4 v[244:247], v252, s[100:101] offset:32
	global_load_dwordx4 v[248:251], v252, s[100:101] offset:48
	s_and_b64 vcc, exec, s[6:7]
	s_mov_b64 s[40:41], 0x1b500000
	v_mov_b32_e32 v98, v104
	v_mul_f32_e32 v104, v96, v108
	v_mul_f32_e32 v120, v88, v109
	v_mul_f32_e32 v108, v88, v108
	v_mul_f32_e32 v122, v96, v109
	v_mov_b32_e32 v88, v97
	v_mov_b32_e32 v96, v89
	v_mov_b32_e32 v124, v112
	v_mul_f32_e32 v112, v92, v116
	v_mul_f32_e32 v126, v84, v117
	v_mul_f32_e32 v116, v84, v116
	v_mul_f32_e32 v128, v92, v117
	v_mov_b32_e32 v84, v93
	v_mov_b32_e32 v92, v85
	v_mov_b32_e32 v99, v106
	v_mov_b32_e32 v106, v105
	v_mov_b32_e32 v125, v114
	v_mov_b32_e32 v114, v113
	v_pk_mul_f32 v[88:89], v[88:89], v[110:111]
	v_pk_mul_f32 v[96:97], v[96:97], v[110:111]
	v_pk_mul_f32 v[150:151], v[84:85], v[118:119]
	v_pk_mul_f32 v[118:119], v[92:93], v[118:119]
	v_pk_mul_f32 v[130:131], v[86:87], v[106:107]
	v_pk_mul_f32 v[106:107], v[94:95], v[106:107]
	v_pk_mul_f32 v[110:111], v[82:83], v[114:115]
	v_pk_mul_f32 v[114:115], v[90:91], v[114:115]
	v_mov_b32_e32 v105, v88
	v_mov_b32_e32 v121, v89
	v_mov_b32_e32 v109, v96
	v_mov_b32_e32 v123, v97
	v_mov_b32_e32 v113, v150
	v_mov_b32_e32 v127, v151
	v_mov_b32_e32 v117, v118
	v_mov_b32_e32 v129, v119
	v_pk_fma_f32 v[92:93], v[94:95], v[98:99], v[130:131] neg_lo:[0,0,1] neg_hi:[0,0,1]
	v_pk_fma_f32 v[84:85], v[86:87], v[98:99], v[106:107]
	v_pk_fma_f32 v[96:97], v[90:91], v[124:125], v[110:111] neg_lo:[0,0,1] neg_hi:[0,0,1]
	v_pk_fma_f32 v[88:89], v[82:83], v[124:125], v[114:115]
	v_pk_add_f32 v[94:95], v[104:105], v[120:121] neg_lo:[0,1] neg_hi:[0,1]
	v_pk_add_f32 v[86:87], v[108:109], v[122:123]
	v_pk_add_f32 v[98:99], v[112:113], v[126:127] neg_lo:[0,1] neg_hi:[0,1]
	v_pk_add_f32 v[90:91], v[116:117], v[128:129]
	s_cbranch_vccnz .LBB0_225
	v_pk_mul_f32 v[94:95], v[94:95], s[28:29] op_sel_hi:[1,0]
	v_pk_mul_f32 v[92:93], v[92:93], s[28:29] op_sel_hi:[1,0]
	v_pk_mul_f32 v[86:87], v[86:87], s[28:29] op_sel_hi:[1,0]
	v_pk_mul_f32 v[84:85], v[84:85], s[28:29] op_sel_hi:[1,0]
	v_pk_mul_f32 v[98:99], v[98:99], s[28:29] op_sel_hi:[1,0]
	v_pk_mul_f32 v[96:97], v[96:97], s[28:29] op_sel_hi:[1,0]
	v_pk_mul_f32 v[90:91], v[90:91], s[28:29] op_sel_hi:[1,0]
	v_pk_mul_f32 v[88:89], v[88:89], s[28:29] op_sel_hi:[1,0]
	s_mov_b64 s[40:41], 0x19300000

; __device__ __forceinline__ u32x4 pack8(const f32x4 a, const f32x4 b) { u32x4 w; w.x = cvt_pk_bf16(a[0], a[1]); w.y = cvt_pk_bf16(a[2], a[3]); w.z = cvt_pk_bf16(b[0], b[1]); w.w = cvt_pk_bf16(b[2], b[3]); return w; }
; __device__ __forceinline__ void rope8(const float* tab64, int row, int fq, const f32x4 x1a, const f32x4 x2a, const f32x4 x1b, const f32x4 x2b, f32x4& a1, f32x4& a2, f32x4& b1, f32x4& b2) {
;     const float* tp = tab64 + ((size_t)pos_index_(row) * 32 + 8 * fq) * 2;
;     const f32x4 c0 = *(const f32x4*)tp, c1 = *(const f32x4*)(tp + 4), c2 = *(const f32x4*)(tp + 8), c3 = *(const f32x4*)(tp + 12);
;     rope4(x1a, x2a, c0, c1, a1, a2); rope4(x1b, x2b, c2, c3, b1, b2);
;     __device__ __forceinline__ void operator()(const f32x4 (&acc)[2][2][4][2], const Unit& u, int wr, int wc, int fr, int fq) const {
;     ...
;             for (int m = 0; m < 4; ++m) {
;                 const int rowb = u.pm * BM + ai * HALF + wr * 64 + m * 16, row0 = rowb + (fr & 7); const size_t ro0 = (size_t)row0 * 2048;
;                 float* f0 = row0 < 8192 ? (type == 1 ? okp : ovp) + ro0 : (type == 1 ? oks : ovs) + (ro0 - (size_t)8192 * 2048);
;                 if (type < 2) {
;                     f32x4 a1, a2, b1, b2; rope8(tab64, rowb + fr, fq, acc[ai][0][m][0], acc[ai][1][m][0], acc[ai][0][m][1], acc[ai][1][m][1], a1, a2, b1, b2);
;                     if (type == 0) { a1 = a1 * qscale; a2 = a2 * qscale; b1 = b1 * qscale; b2 = b2 * qscale; }
;                     st2_bf16((type == 0 ? QA : KA) + ro0 + cw + (lo ? 0 : 32), 8 * 2048, pack8(a1, b1), pack8(a2, b2), lo, dry);
;                     if (type == 1) { st2_f32<true>(f0 + cw + (lo ? 0 : 4), 8 * 2048, a1, b1, lo, dry); st2_f32<true>(f0 + cw + 32 + (lo ? 0 : 4), 8 * 2048, a2, b2, lo, dry); }
.LBB0_237:
	s_andn2_b64 vcc, exec, s[40:41]
	s_cbranch_vccnz .LBB0_242
.LBB0_238:
	s_andn2_b64 vcc, exec, s[0:1]
	s_cbranch_vccnz .Lrope_q_p1_3
	s_waitcnt vmcnt(6)
	s_branch .Lrope_j_p1_3

; __device__ __forceinline__ u32x4 pack8(const f32x4 a, const f32x4 b) { u32x4 w; w.x = cvt_pk_bf16(a[0], a[1]); w.y = cvt_pk_bf16(a[2], a[3]); w.z = cvt_pk_bf16(b[0], b[1]); w.w = cvt_pk_bf16(b[2], b[3]); return w; }
; __device__ __forceinline__ void rope8(const float* tab64, int row, int fq, const f32x4 x1a, const f32x4 x2a, const f32x4 x1b, const f32x4 x2b, f32x4& a1, f32x4& a2, f32x4& b1, f32x4& b2) {
;     const float* tp = tab64 + ((size_t)pos_index_(row) * 32 + 8 * fq) * 2;
;     const f32x4 c0 = *(const f32x4*)tp, c1 = *(const f32x4*)(tp + 4), c2 = *(const f32x4*)(tp + 8), c3 = *(const f32x4*)(tp + 12);
;     rope4(x1a, x2a, c0, c1, a1, a2); rope4(x1b, x2b, c2, c3, b1, b2);
;     __device__ __forceinline__ void operator()(const f32x4 (&acc)[2][2][4][2], const Unit& u, int wr, int wc, int fr, int fq) const {
;     ...
;             for (int m = 0; m < 4; ++m) {
;                 const int rowb = u.pm * BM + ai * HALF + wr * 64 + m * 16, row0 = rowb + (fr & 7); const size_t ro0 = (size_t)row0 * 2048;
;                 float* f0 = row0 < 8192 ? (type == 1 ? okp : ovp) + ro0 : (type == 1 ? oks : ovs) + (ro0 - (size_t)8192 * 2048);
;                 if (type < 2) {
;                     f32x4 a1, a2, b1, b2; rope8(tab64, rowb + fr, fq, acc[ai][0][m][0], acc[ai][1][m][0], acc[ai][0][m][1], acc[ai][1][m][1], a1, a2, b1, b2);
;                     if (type == 0) { a1 = a1 * qscale; a2 = a2 * qscale; b1 = b1 * qscale; b2 = b2 * qscale; }
;                     st2_bf16((type == 0 ? QA : KA) + ro0 + cw + (lo ? 0 : 32), 8 * 2048, pack8(a1, b1), pack8(a2, b2), lo, dry);
;                     if (type == 1) { st2_f32<true>(f0 + cw + (lo ? 0 : 4), 8 * 2048, a1, b1, lo, dry); st2_f32<true>(f0 + cw + 32 + (lo ? 0 : 4), 8 * 2048, a2, b2, lo, dry); }
.Lrope_j_p1_3:
	v_mov_b64_e32 v[88:89], v[236:237]
	v_mov_b64_e32 v[90:91], v[238:239]
	v_mov_b64_e32 v[92:93], v[240:241]
	v_mov_b64_e32 v[94:95], v[242:243]
	v_mov_b64_e32 v[96:97], v[244:245]
	v_mov_b64_e32 v[98:99], v[246:247]
	v_mov_b64_e32 v[100:101], v[248:249]
	v_mov_b64_e32 v[102:103], v[250:251]
	v_readlane_b32 s100, v254, 22
	v_readlane_b32 s101, v254, 23
	s_add_i32 s98, s31, 0x80
	v_or_b32_e32 v252, s98, v141
	v_bitop3_b32 v253, s98, v161, v141 bitop3:0xc8
	v_cmp_gt_i32_e32 vcc, s49, v252
	v_cndmask_b32_e32 v252, v155, v253, vcc
	v_lshl_or_b32 v252, v252, 8, v168
	s_nop 2
	global_load_dwordx4 v[236:239], v252, s[100:101]
	global_load_dwordx4 v[240:243], v252, s[100:101] offset:16
	global_load_dwordx4 v[244:247], v252, s[100:101] offset:32
	global_load_dwordx4 v[248:251], v252, s[100:101] offset:48
	s_and_b64 vcc, exec, s[6:7]
	s_mov_b64 s[40:41], 0x1b500000
	v_mov_b32_e32 v82, v88
	v_mul_f32_e32 v88, v80, v92
	v_mul_f32_e32 v104, v72, v93
	v_mul_f32_e32 v92, v72, v92
	v_mul_f32_e32 v106, v80, v93
	v_mov_b32_e32 v72, v81
	v_mov_b32_e32 v80, v73
	v_mov_b32_e32 v108, v96
	v_mul_f32_e32 v96, v76, v100
	v_mul_f32_e32 v110, v68, v101
	v_mul_f32_e32 v100, v68, v100
	v_mul_f32_e32 v112, v76, v101
	v_mov_b32_e32 v68, v77
	v_mov_b32_e32 v76, v69
	v_mov_b32_e32 v83, v90
	v_mov_b32_e32 v90, v89
	v_mov_b32_e32 v109, v98
	v_mov_b32_e32 v98, v97
	v_pk_mul_f32 v[72:73], v[72:73], v[94:95]
	v_pk_mul_f32 v[80:81], v[80:81], v[94:95]
	v_pk_mul_f32 v[116:117], v[68:69], v[102:103]
	v_pk_mul_f32 v[102:103], v[76:77], v[102:103]
	v_pk_mul_f32 v[114:115], v[70:71], v[90:91]
	v_pk_mul_f32 v[90:91], v[78:79], v[90:91]
	v_pk_mul_f32 v[94:95], v[66:67], v[98:99]
	v_pk_mul_f32 v[98:99], v[74:75], v[98:99]
	v_mov_b32_e32 v89, v72
	v_mov_b32_e32 v105, v73
	v_mov_b32_e32 v93, v80
	v_mov_b32_e32 v107, v81
	v_mov_b32_e32 v97, v116
	v_mov_b32_e32 v111, v117
	v_mov_b32_e32 v101, v102
	v_mov_b32_e32 v113, v103
	v_pk_fma_f32 v[76:77], v[78:79], v[82:83], v[114:115] neg_lo:[0,0,1] neg_hi:[0,0,1]
	v_pk_fma_f32 v[68:69], v[70:71], v[82:83], v[90:91]
	v_pk_fma_f32 v[80:81], v[74:75], v[108:109], v[94:95] neg_lo:[0,0,1] neg_hi:[0,0,1]
	v_pk_fma_f32 v[72:73], v[66:67], v[108:109], v[98:99]
	v_pk_add_f32 v[78:79], v[88:89], v[104:105] neg_lo:[0,1] neg_hi:[0,1]
	v_pk_add_f32 v[70:71], v[92:93], v[106:107]
	v_pk_add_f32 v[82:83], v[96:97], v[110:111] neg_lo:[0,1] neg_hi:[0,1]
	v_pk_add_f32 v[74:75], v[100:101], v[112:113]
	s_cbranch_vccnz .LBB0_240
	v_pk_mul_f32 v[78:79], v[78:79], s[28:29] op_sel_hi:[1,0]
	v_pk_mul_f32 v[76:77], v[76:77], s[28:29] op_sel_hi:[1,0]
	v_pk_mul_f32 v[70:71], v[70:71], s[28:29] op_sel_hi:[1,0]
	v_pk_mul_f32 v[68:69], v[68:69], s[28:29] op_sel_hi:[1,0]
	v_pk_mul_f32 v[82:83], v[82:83], s[28:29] op_sel_hi:[1,0]
	v_pk_mul_f32 v[80:81], v[80:81], s[28:29] op_sel_hi:[1,0]
	v_pk_mul_f32 v[74:75], v[74:75], s[28:29] op_sel_hi:[1,0]
	v_pk_mul_f32 v[72:73], v[72:73], s[28:29] op_sel_hi:[1,0]
	s_mov_b64 s[40:41], 0x19300000

; __device__ __forceinline__ u32x4 pack8(const f32x4 a, const f32x4 b) { u32x4 w; w.x = cvt_pk_bf16(a[0], a[1]); w.y = cvt_pk_bf16(a[2], a[3]); w.z = cvt_pk_bf16(b[0], b[1]); w.w = cvt_pk_bf16(b[2], b[3]); return w; }
; __device__ __forceinline__ void rope8(const float* tab64, int row, int fq, const f32x4 x1a, const f32x4 x2a, const f32x4 x1b, const f32x4 x2b, f32x4& a1, f32x4& a2, f32x4& b1, f32x4& b2) {
;     const float* tp = tab64 + ((size_t)pos_index_(row) * 32 + 8 * fq) * 2;
;     const f32x4 c0 = *(const f32x4*)tp, c1 = *(const f32x4*)(tp + 4), c2 = *(const f32x4*)(tp + 8), c3 = *(const f32x4*)(tp + 12);
;     rope4(x1a, x2a, c0, c1, a1, a2); rope4(x1b, x2b, c2, c3, b1, b2);
;     __device__ __forceinline__ void operator()(const f32x4 (&acc)[2][2][4][2], const Unit& u, int wr, int wc, int fr, int fq) const {
;     ...
;             for (int m = 0; m < 4; ++m) {
;                 const int rowb = u.pm * BM + ai * HALF + wr * 64 + m * 16, row0 = rowb + (fr & 7); const size_t ro0 = (size_t)row0 * 2048;
;                 float* f0 = row0 < 8192 ? (type == 1 ? okp : ovp) + ro0 : (type == 1 ? oks : ovs) + (ro0 - (size_t)8192 * 2048);
;                 if (type < 2) {
;                     f32x4 a1, a2, b1, b2; rope8(tab64, rowb + fr, fq, acc[ai][0][m][0], acc[ai][1][m][0], acc[ai][0][m][1], acc[ai][1][m][1], a1, a2, b1, b2);
;                     if (type == 0) { a1 = a1 * qscale; a2 = a2 * qscale; b1 = b1 * qscale; b2 = b2 * qscale; }
;                     st2_bf16((type == 0 ? QA : KA) + ro0 + cw + (lo ? 0 : 32), 8 * 2048, pack8(a1, b1), pack8(a2, b2), lo, dry);
;                     if (type == 1) { st2_f32<true>(f0 + cw + (lo ? 0 : 4), 8 * 2048, a1, b1, lo, dry); st2_f32<true>(f0 + cw + 32 + (lo ? 0 : 4), 8 * 2048, a2, b2, lo, dry); }
.LBB0_252:
	s_andn2_b64 vcc, exec, s[40:41]
	s_cbranch_vccnz .LBB0_257
.LBB0_253:
	s_andn2_b64 vcc, exec, s[0:1]
	s_cbranch_vccnz .Lrope_q_p1_4
	s_waitcnt vmcnt(6)
	s_branch .Lrope_j_p1_4

; __device__ __forceinline__ u32x4 pack8(const f32x4 a, const f32x4 b) { u32x4 w; w.x = cvt_pk_bf16(a[0], a[1]); w.y = cvt_pk_bf16(a[2], a[3]); w.z = cvt_pk_bf16(b[0], b[1]); w.w = cvt_pk_bf16(b[2], b[3]); return w; }
; __device__ __forceinline__ void rope8(const float* tab64, int row, int fq, const f32x4 x1a, const f32x4 x2a, const f32x4 x1b, const f32x4 x2b, f32x4& a1, f32x4& a2, f32x4& b1, f32x4& b2) {
;     const float* tp = tab64 + ((size_t)pos_index_(row) * 32 + 8 * fq) * 2;
;     const f32x4 c0 = *(const f32x4*)tp, c1 = *(const f32x4*)(tp + 4), c2 = *(const f32x4*)(tp + 8), c3 = *(const f32x4*)(tp + 12);
;     rope4(x1a, x2a, c0, c1, a1, a2); rope4(x1b, x2b, c2, c3, b1, b2);
;     __device__ __forceinline__ void operator()(const f32x4 (&acc)[2][2][4][2], const Unit& u, int wr, int wc, int fr, int fq) const {
;     ...
;             for (int m = 0; m < 4; ++m) {
;                 const int rowb = u.pm * BM + ai * HALF + wr * 64 + m * 16, row0 = rowb + (fr & 7); const size_t ro0 = (size_t)row0 * 2048;
;                 float* f0 = row0 < 8192 ? (type == 1 ? okp : ovp) + ro0 : (type == 1 ? oks : ovs) + (ro0 - (size_t)8192 * 2048);
;                 if (type < 2) {
;                     f32x4 a1, a2, b1, b2; rope8(tab64, rowb + fr, fq, acc[ai][0][m][0], acc[ai][1][m][0], acc[ai][0][m][1], acc[ai][1][m][1], a1, a2, b1, b2);
;                     if (type == 0) { a1 = a1 * qscale; a2 = a2 * qscale; b1 = b1 * qscale; b2 = b2 * qscale; }
;                     st2_bf16((type == 0 ? QA : KA) + ro0 + cw + (lo ? 0 : 32), 8 * 2048, pack8(a1, b1), pack8(a2, b2), lo, dry);
;                     if (type == 1) { st2_f32<true>(f0 + cw + (lo ? 0 : 4), 8 * 2048, a1, b1, lo, dry); st2_f32<true>(f0 + cw + 32 + (lo ? 0 : 4), 8 * 2048, a2, b2, lo, dry); }
.Lrope_j_p1_4:
	v_mov_b64_e32 v[72:73], v[236:237]
	v_mov_b64_e32 v[74:75], v[238:239]
	v_mov_b64_e32 v[76:77], v[240:241]
	v_mov_b64_e32 v[78:79], v[242:243]
	v_mov_b64_e32 v[80:81], v[244:245]
	v_mov_b64_e32 v[82:83], v[246:247]
	v_mov_b64_e32 v[84:85], v[248:249]
	v_mov_b64_e32 v[86:87], v[250:251]
	v_readlane_b32 s100, v254, 22
	v_readlane_b32 s101, v254, 23
	s_add_i32 s98, s31, 0x90
	v_or_b32_e32 v252, s98, v141
	v_bitop3_b32 v253, s98, v162, v141 bitop3:0xc8
	v_and_or_b32 v236, v252, 31, v163
	v_cmp_gt_i32_e32 vcc, s49, v252
	v_cndmask_b32_e32 v252, v236, v253, vcc
	v_lshl_or_b32 v252, v252, 8, v168
	s_nop 2
	global_load_dwordx4 v[236:239], v252, s[100:101]
	global_load_dwordx4 v[240:243], v252, s[100:101] offset:16
	global_load_dwordx4 v[244:247], v252, s[100:101] offset:32
	global_load_dwordx4 v[248:251], v252, s[100:101] offset:48
	s_and_b64 vcc, exec, s[6:7]
	s_mov_b64 s[40:41], 0x1b500000
	v_mov_b32_e32 v66, v72
	v_mul_f32_e32 v72, v64, v76
	v_mul_f32_e32 v88, v56, v77
	v_mul_f32_e32 v76, v56, v76
	v_mul_f32_e32 v90, v64, v77
	v_mov_b32_e32 v56, v65
	v_mov_b32_e32 v64, v57
	v_mov_b32_e32 v92, v80
	v_mul_f32_e32 v80, v60, v84
	v_mul_f32_e32 v94, v52, v85
	v_mul_f32_e32 v84, v52, v84
	v_mul_f32_e32 v96, v60, v85
	v_mov_b32_e32 v52, v61
	v_mov_b32_e32 v60, v53
	v_mov_b32_e32 v67, v74
	v_mov_b32_e32 v74, v73
	v_mov_b32_e32 v93, v82
	v_mov_b32_e32 v82, v81
	v_pk_mul_f32 v[56:57], v[56:57], v[78:79]
	v_pk_mul_f32 v[64:65], v[64:65], v[78:79]
	v_pk_mul_f32 v[100:101], v[52:53], v[86:87]
	v_pk_mul_f32 v[86:87], v[60:61], v[86:87]
	v_pk_mul_f32 v[98:99], v[54:55], v[74:75]
	v_pk_mul_f32 v[74:75], v[62:63], v[74:75]
	v_pk_mul_f32 v[78:79], v[50:51], v[82:83]
	v_pk_mul_f32 v[82:83], v[58:59], v[82:83]
	v_mov_b32_e32 v73, v56
	v_mov_b32_e32 v89, v57
	v_mov_b32_e32 v77, v64
	v_mov_b32_e32 v91, v65
	v_mov_b32_e32 v81, v100
	v_mov_b32_e32 v95, v101
	v_mov_b32_e32 v85, v86
	v_mov_b32_e32 v97, v87
	v_pk_fma_f32 v[60:61], v[62:63], v[66:67], v[98:99] neg_lo:[0,0,1] neg_hi:[0,0,1]
	v_pk_fma_f32 v[52:53], v[54:55], v[66:67], v[74:75]
	v_pk_fma_f32 v[64:65], v[58:59], v[92:93], v[78:79] neg_lo:[0,0,1] neg_hi:[0,0,1]
	v_pk_fma_f32 v[56:57], v[50:51], v[92:93], v[82:83]
	v_pk_add_f32 v[62:63], v[72:73], v[88:89] neg_lo:[0,1] neg_hi:[0,1]
	v_pk_add_f32 v[54:55], v[76:77], v[90:91]
	v_pk_add_f32 v[66:67], v[80:81], v[94:95] neg_lo:[0,1] neg_hi:[0,1]
	v_pk_add_f32 v[58:59], v[84:85], v[96:97]
	s_cbranch_vccnz .LBB0_255
	v_pk_mul_f32 v[62:63], v[62:63], s[28:29] op_sel_hi:[1,0]
	v_pk_mul_f32 v[60:61], v[60:61], s[28:29] op_sel_hi:[1,0]
	v_pk_mul_f32 v[54:55], v[54:55], s[28:29] op_sel_hi:[1,0]
	v_pk_mul_f32 v[52:53], v[52:53], s[28:29] op_sel_hi:[1,0]
	v_pk_mul_f32 v[66:67], v[66:67], s[28:29] op_sel_hi:[1,0]
	v_pk_mul_f32 v[64:65], v[64:65], s[28:29] op_sel_hi:[1,0]
	v_pk_mul_f32 v[58:59], v[58:59], s[28:29] op_sel_hi:[1,0]
	v_pk_mul_f32 v[56:57], v[56:57], s[28:29] op_sel_hi:[1,0]
	s_mov_b64 s[40:41], 0x19300000

; __device__ __forceinline__ u32x4 pack8(const f32x4 a, const f32x4 b) { u32x4 w; w.x = cvt_pk_bf16(a[0], a[1]); w.y = cvt_pk_bf16(a[2], a[3]); w.z = cvt_pk_bf16(b[0], b[1]); w.w = cvt_pk_bf16(b[2], b[3]); return w; }
; __device__ __forceinline__ void rope8(const float* tab64, int row, int fq, const f32x4 x1a, const f32x4 x2a, const f32x4 x1b, const f32x4 x2b, f32x4& a1, f32x4& a2, f32x4& b1, f32x4& b2) {
;     const float* tp = tab64 + ((size_t)pos_index_(row) * 32 + 8 * fq) * 2;
;     const f32x4 c0 = *(const f32x4*)tp, c1 = *(const f32x4*)(tp + 4), c2 = *(const f32x4*)(tp + 8), c3 = *(const f32x4*)(tp + 12);
;     rope4(x1a, x2a, c0, c1, a1, a2); rope4(x1b, x2b, c2, c3, b1, b2);
;     __device__ __forceinline__ void operator()(const f32x4 (&acc)[2][2][4][2], const Unit& u, int wr, int wc, int fr, int fq) const {
;     ...
;             for (int m = 0; m < 4; ++m) {
;                 const int rowb = u.pm * BM + ai * HALF + wr * 64 + m * 16, row0 = rowb + (fr & 7); const size_t ro0 = (size_t)row0 * 2048;
;                 float* f0 = row0 < 8192 ? (type == 1 ? okp : ovp) + ro0 : (type == 1 ? oks : ovs) + (ro0 - (size_t)8192 * 2048);
;                 if (type < 2) {
;                     f32x4 a1, a2, b1, b2; rope8(tab64, rowb + fr, fq, acc[ai][0][m][0], acc[ai][1][m][0], acc[ai][0][m][1], acc[ai][1][m][1], a1, a2, b1, b2);
;                     if (type == 0) { a1 = a1 * qscale; a2 = a2 * qscale; b1 = b1 * qscale; b2 = b2 * qscale; }
;                     st2_bf16((type == 0 ? QA : KA) + ro0 + cw + (lo ? 0 : 32), 8 * 2048, pack8(a1, b1), pack8(a2, b2), lo, dry);
;                     if (type == 1) { st2_f32<true>(f0 + cw + (lo ? 0 : 4), 8 * 2048, a1, b1, lo, dry); st2_f32<true>(f0 + cw + 32 + (lo ? 0 : 4), 8 * 2048, a2, b2, lo, dry); }
.LBB0_267:
	s_andn2_b64 vcc, exec, s[40:41]
	s_cbranch_vccnz .LBB0_272
.LBB0_268:
	s_andn2_b64 vcc, exec, s[0:1]
	s_cbranch_vccnz .Lrope_q_p1_5
	s_waitcnt vmcnt(6)
	s_branch .Lrope_j_p1_5

; __device__ __forceinline__ u32x4 pack8(const f32x4 a, const f32x4 b) { u32x4 w; w.x = cvt_pk_bf16(a[0], a[1]); w.y = cvt_pk_bf16(a[2], a[3]); w.z = cvt_pk_bf16(b[0], b[1]); w.w = cvt_pk_bf16(b[2], b[3]); return w; }
; __device__ __forceinline__ void rope8(const float* tab64, int row, int fq, const f32x4 x1a, const f32x4 x2a, const f32x4 x1b, const f32x4 x2b, f32x4& a1, f32x4& a2, f32x4& b1, f32x4& b2) {
;     const float* tp = tab64 + ((size_t)pos_index_(row) * 32 + 8 * fq) * 2;
;     const f32x4 c0 = *(const f32x4*)tp, c1 = *(const f32x4*)(tp + 4), c2 = *(const f32x4*)(tp + 8), c3 = *(const f32x4*)(tp + 12);
;     rope4(x1a, x2a, c0, c1, a1, a2); rope4(x1b, x2b, c2, c3, b1, b2);
;     __device__ __forceinline__ void operator()(const f32x4 (&acc)[2][2][4][2], const Unit& u, int wr, int wc, int fr, int fq) const {
;     ...
;             for (int m = 0; m < 4; ++m) {
;                 const int rowb = u.pm * BM + ai * HALF + wr * 64 + m * 16, row0 = rowb + (fr & 7); const size_t ro0 = (size_t)row0 * 2048;
;                 float* f0 = row0 < 8192 ? (type == 1 ? okp : ovp) + ro0 : (type == 1 ? oks : ovs) + (ro0 - (size_t)8192 * 2048);
;                 if (type < 2) {
;                     f32x4 a1, a2, b1, b2; rope8(tab64, rowb + fr, fq, acc[ai][0][m][0], acc[ai][1][m][0], acc[ai][0][m][1], acc[ai][1][m][1], a1, a2, b1, b2);
;                     if (type == 0) { a1 = a1 * qscale; a2 = a2 * qscale; b1 = b1 * qscale; b2 = b2 * qscale; }
;                     st2_bf16((type == 0 ? QA : KA) + ro0 + cw + (lo ? 0 : 32), 8 * 2048, pack8(a1, b1), pack8(a2, b2), lo, dry);
;                     if (type == 1) { st2_f32<true>(f0 + cw + (lo ? 0 : 4), 8 * 2048, a1, b1, lo, dry); st2_f32<true>(f0 + cw + 32 + (lo ? 0 : 4), 8 * 2048, a2, b2, lo, dry); }
.Lrope_j_p1_5:
	v_mov_b64_e32 v[56:57], v[236:237]
	v_mov_b64_e32 v[58:59], v[238:239]
	v_mov_b64_e32 v[60:61], v[240:241]
	v_mov_b64_e32 v[62:63], v[242:243]
	v_mov_b64_e32 v[64:65], v[244:245]
	v_mov_b64_e32 v[66:67], v[246:247]
	v_mov_b64_e32 v[68:69], v[248:249]
	v_mov_b64_e32 v[70:71], v[250:251]
	v_readlane_b32 s100, v254, 22
	v_readlane_b32 s101, v254, 23
	s_add_i32 s98, s31, 0xa0
	v_or_b32_e32 v252, s98, v141
	v_bitop3_b32 v253, s98, v165, v141 bitop3:0xc8
	v_and_or_b32 v236, v252, 47, v163
	v_cmp_gt_i32_e32 vcc, s49, v252
	v_cndmask_b32_e32 v252, v236, v253, vcc
	v_lshl_or_b32 v252, v252, 8, v168
	s_nop 2
	global_load_dwordx4 v[236:239], v252, s[100:101]
	global_load_dwordx4 v[240:243], v252, s[100:101] offset:16
	global_load_dwordx4 v[244:247], v252, s[100:101] offset:32
	global_load_dwordx4 v[248:251], v252, s[100:101] offset:48
	s_and_b64 vcc, exec, s[6:7]
	s_mov_b64 s[40:41], 0x1b500000
	v_mov_b32_e32 v50, v56
	v_mul_f32_e32 v56, v48, v60
	v_mul_f32_e32 v72, v40, v61
	v_mul_f32_e32 v60, v40, v60
	v_mul_f32_e32 v74, v48, v61
	v_mov_b32_e32 v40, v49
	v_mov_b32_e32 v48, v41
	v_mov_b32_e32 v76, v64
	v_mul_f32_e32 v64, v44, v68
	v_mul_f32_e32 v78, v36, v69
	v_mul_f32_e32 v68, v36, v68
	v_mul_f32_e32 v80, v44, v69
	v_mov_b32_e32 v36, v45
	v_mov_b32_e32 v44, v37
	v_mov_b32_e32 v51, v58
	v_mov_b32_e32 v58, v57
	v_mov_b32_e32 v77, v66
	v_mov_b32_e32 v66, v65
	v_pk_mul_f32 v[40:41], v[40:41], v[62:63]
	v_pk_mul_f32 v[48:49], v[48:49], v[62:63]
	v_pk_mul_f32 v[84:85], v[36:37], v[70:71]
	v_pk_mul_f32 v[70:71], v[44:45], v[70:71]
	v_pk_mul_f32 v[82:83], v[38:39], v[58:59]
	v_pk_mul_f32 v[58:59], v[46:47], v[58:59]
	v_pk_mul_f32 v[62:63], v[34:35], v[66:67]
	v_pk_mul_f32 v[66:67], v[42:43], v[66:67]
	v_mov_b32_e32 v57, v40
	v_mov_b32_e32 v73, v41
	v_mov_b32_e32 v61, v48
	v_mov_b32_e32 v75, v49
	v_mov_b32_e32 v65, v84
	v_mov_b32_e32 v79, v85
	v_mov_b32_e32 v69, v70
	v_mov_b32_e32 v81, v71
	v_pk_fma_f32 v[44:45], v[46:47], v[50:51], v[82:83] neg_lo:[0,0,1] neg_hi:[0,0,1]
	v_pk_fma_f32 v[36:37], v[38:39], v[50:51], v[58:59]
	v_pk_fma_f32 v[48:49], v[42:43], v[76:77], v[62:63] neg_lo:[0,0,1] neg_hi:[0,0,1]
	v_pk_fma_f32 v[40:41], v[34:35], v[76:77], v[66:67]
	v_pk_add_f32 v[46:47], v[56:57], v[72:73] neg_lo:[0,1] neg_hi:[0,1]
	v_pk_add_f32 v[38:39], v[60:61], v[74:75]
	v_pk_add_f32 v[50:51], v[64:65], v[78:79] neg_lo:[0,1] neg_hi:[0,1]
	v_pk_add_f32 v[42:43], v[68:69], v[80:81]
	s_cbranch_vccnz .LBB0_270
	v_pk_mul_f32 v[46:47], v[46:47], s[28:29] op_sel_hi:[1,0]
	v_pk_mul_f32 v[44:45], v[44:45], s[28:29] op_sel_hi:[1,0]
	v_pk_mul_f32 v[38:39], v[38:39], s[28:29] op_sel_hi:[1,0]
	v_pk_mul_f32 v[36:37], v[36:37], s[28:29] op_sel_hi:[1,0]
	v_pk_mul_f32 v[50:51], v[50:51], s[28:29] op_sel_hi:[1,0]
	v_pk_mul_f32 v[48:49], v[48:49], s[28:29] op_sel_hi:[1,0]
	v_pk_mul_f32 v[42:43], v[42:43], s[28:29] op_sel_hi:[1,0]
	v_pk_mul_f32 v[40:41], v[40:41], s[28:29] op_sel_hi:[1,0]
	s_mov_b64 s[40:41], 0x19300000

; __device__ __forceinline__ u32x4 pack8(const f32x4 a, const f32x4 b) { u32x4 w; w.x = cvt_pk_bf16(a[0], a[1]); w.y = cvt_pk_bf16(a[2], a[3]); w.z = cvt_pk_bf16(b[0], b[1]); w.w = cvt_pk_bf16(b[2], b[3]); return w; }
; __device__ __forceinline__ void rope8(const float* tab64, int row, int fq, const f32x4 x1a, const f32x4 x2a, const f32x4 x1b, const f32x4 x2b, f32x4& a1, f32x4& a2, f32x4& b1, f32x4& b2) {
;     const float* tp = tab64 + ((size_t)pos_index_(row) * 32 + 8 * fq) * 2;
;     const f32x4 c0 = *(const f32x4*)tp, c1 = *(const f32x4*)(tp + 4), c2 = *(const f32x4*)(tp + 8), c3 = *(const f32x4*)(tp + 12);
;     rope4(x1a, x2a, c0, c1, a1, a2); rope4(x1b, x2b, c2, c3, b1, b2);
;     __device__ __forceinline__ void operator()(const f32x4 (&acc)[2][2][4][2], const Unit& u, int wr, int wc, int fr, int fq) const {
;     ...
;             for (int m = 0; m < 4; ++m) {
;                 const int rowb = u.pm * BM + ai * HALF + wr * 64 + m * 16, row0 = rowb + (fr & 7); const size_t ro0 = (size_t)row0 * 2048;
;                 float* f0 = row0 < 8192 ? (type == 1 ? okp : ovp) + ro0 : (type == 1 ? oks : ovs) + (ro0 - (size_t)8192 * 2048);
;                 if (type < 2) {
;                     f32x4 a1, a2, b1, b2; rope8(tab64, rowb + fr, fq, acc[ai][0][m][0], acc[ai][1][m][0], acc[ai][0][m][1], acc[ai][1][m][1], a1, a2, b1, b2);
;                     if (type == 0) { a1 = a1 * qscale; a2 = a2 * qscale; b1 = b1 * qscale; b2 = b2 * qscale; }
;                     st2_bf16((type == 0 ? QA : KA) + ro0 + cw + (lo ? 0 : 32), 8 * 2048, pack8(a1, b1), pack8(a2, b2), lo, dry);
;                     if (type == 1) { st2_f32<true>(f0 + cw + (lo ? 0 : 4), 8 * 2048, a1, b1, lo, dry); st2_f32<true>(f0 + cw + 32 + (lo ? 0 : 4), 8 * 2048, a2, b2, lo, dry); }
.LBB0_282:
	s_andn2_b64 vcc, exec, s[40:41]
	s_cbranch_vccnz .LBB0_287
.LBB0_283:
	s_andn2_b64 vcc, exec, s[0:1]
	s_cbranch_vccnz .Lrope_q_p1_6
	s_waitcnt vmcnt(6)
	s_branch .Lrope_j_p1_6

; __device__ __forceinline__ u32x4 pack8(const f32x4 a, const f32x4 b) { u32x4 w; w.x = cvt_pk_bf16(a[0], a[1]); w.y = cvt_pk_bf16(a[2], a[3]); w.z = cvt_pk_bf16(b[0], b[1]); w.w = cvt_pk_bf16(b[2], b[3]); return w; }
; __device__ __forceinline__ void rope8(const float* tab64, int row, int fq, const f32x4 x1a, const f32x4 x2a, const f32x4 x1b, const f32x4 x2b, f32x4& a1, f32x4& a2, f32x4& b1, f32x4& b2) {
;     const float* tp = tab64 + ((size_t)pos_index_(row) * 32 + 8 * fq) * 2;
;     const f32x4 c0 = *(const f32x4*)tp, c1 = *(const f32x4*)(tp + 4), c2 = *(const f32x4*)(tp + 8), c3 = *(const f32x4*)(tp + 12);
;     rope4(x1a, x2a, c0, c1, a1, a2); rope4(x1b, x2b, c2, c3, b1, b2);
;     __device__ __forceinline__ void operator()(const f32x4 (&acc)[2][2][4][2], const Unit& u, int wr, int wc, int fr, int fq) const {
;     ...
;             for (int m = 0; m < 4; ++m) {
;                 const int rowb = u.pm * BM + ai * HALF + wr * 64 + m * 16, row0 = rowb + (fr & 7); const size_t ro0 = (size_t)row0 * 2048;
;                 float* f0 = row0 < 8192 ? (type == 1 ? okp : ovp) + ro0 : (type == 1 ? oks : ovs) + (ro0 - (size_t)8192 * 2048);
;                 if (type < 2) {
;                     f32x4 a1, a2, b1, b2; rope8(tab64, rowb + fr, fq, acc[ai][0][m][0], acc[ai][1][m][0], acc[ai][0][m][1], acc[ai][1][m][1], a1, a2, b1, b2);
;                     if (type == 0) { a1 = a1 * qscale; a2 = a2 * qscale; b1 = b1 * qscale; b2 = b2 * qscale; }
;                     st2_bf16((type == 0 ? QA : KA) + ro0 + cw + (lo ? 0 : 32), 8 * 2048, pack8(a1, b1), pack8(a2, b2), lo, dry);
;                     if (type == 1) { st2_f32<true>(f0 + cw + (lo ? 0 : 4), 8 * 2048, a1, b1, lo, dry); st2_f32<true>(f0 + cw + 32 + (lo ? 0 : 4), 8 * 2048, a2, b2, lo, dry); }
.Lrope_j_p1_6:
	v_mov_b64_e32 v[40:41], v[236:237]
	v_mov_b64_e32 v[42:43], v[238:239]
	v_mov_b64_e32 v[44:45], v[240:241]
	v_mov_b64_e32 v[46:47], v[242:243]
	v_mov_b64_e32 v[48:49], v[244:245]
	v_mov_b64_e32 v[50:51], v[246:247]
	v_mov_b64_e32 v[52:53], v[248:249]
	v_mov_b64_e32 v[54:55], v[250:251]
	v_readlane_b32 s100, v254, 22
	v_readlane_b32 s101, v254, 23
	s_add_i32 s98, s31, 0xb0
	v_or_b32_e32 v252, s98, v141
	v_bitop3_b32 v253, s98, v166, v141 bitop3:0xc8
	v_and_or_b32 v236, v252, 63, v163
	v_cmp_gt_i32_e32 vcc, s49, v252
	v_cndmask_b32_e32 v252, v236, v253, vcc
	v_lshl_or_b32 v252, v252, 8, v168
	s_nop 2
	global_load_dwordx4 v[236:239], v252, s[100:101]
	global_load_dwordx4 v[240:243], v252, s[100:101] offset:16
	global_load_dwordx4 v[244:247], v252, s[100:101] offset:32
	global_load_dwordx4 v[248:251], v252, s[100:101] offset:48
	s_and_b64 vcc, exec, s[6:7]
	s_mov_b64 s[40:41], 0x1b500000
	v_mov_b32_e32 v34, v40
	v_mul_f32_e32 v40, v32, v44
	v_mul_f32_e32 v56, v24, v45
	v_mul_f32_e32 v44, v24, v44
	v_mul_f32_e32 v58, v32, v45
	v_mov_b32_e32 v24, v33
	v_mov_b32_e32 v32, v25
	v_mov_b32_e32 v60, v48
	v_mul_f32_e32 v48, v28, v52
	v_mul_f32_e32 v62, v20, v53
	v_mul_f32_e32 v52, v20, v52
	v_mul_f32_e32 v64, v28, v53
	v_mov_b32_e32 v20, v29
	v_mov_b32_e32 v28, v21
	v_mov_b32_e32 v35, v42
	v_mov_b32_e32 v42, v41
	v_mov_b32_e32 v61, v50
	v_mov_b32_e32 v50, v49
	v_pk_mul_f32 v[24:25], v[24:25], v[46:47]
	v_pk_mul_f32 v[32:33], v[32:33], v[46:47]
	v_pk_mul_f32 v[68:69], v[20:21], v[54:55]
	v_pk_mul_f32 v[54:55], v[28:29], v[54:55]
	v_pk_mul_f32 v[66:67], v[22:23], v[42:43]
	v_pk_mul_f32 v[42:43], v[30:31], v[42:43]
	v_pk_mul_f32 v[46:47], v[18:19], v[50:51]
	v_pk_mul_f32 v[50:51], v[26:27], v[50:51]
	v_mov_b32_e32 v41, v24
	v_mov_b32_e32 v57, v25
	v_mov_b32_e32 v45, v32
	v_mov_b32_e32 v59, v33
	v_mov_b32_e32 v49, v68
	v_mov_b32_e32 v63, v69
	v_mov_b32_e32 v53, v54
	v_mov_b32_e32 v65, v55
	v_pk_fma_f32 v[28:29], v[30:31], v[34:35], v[66:67] neg_lo:[0,0,1] neg_hi:[0,0,1]
	v_pk_fma_f32 v[20:21], v[22:23], v[34:35], v[42:43]
	v_pk_fma_f32 v[32:33], v[26:27], v[60:61], v[46:47] neg_lo:[0,0,1] neg_hi:[0,0,1]
	v_pk_fma_f32 v[24:25], v[18:19], v[60:61], v[50:51]
	v_pk_add_f32 v[30:31], v[40:41], v[56:57] neg_lo:[0,1] neg_hi:[0,1]
	v_pk_add_f32 v[22:23], v[44:45], v[58:59]
	v_pk_add_f32 v[34:35], v[48:49], v[62:63] neg_lo:[0,1] neg_hi:[0,1]
	v_pk_add_f32 v[26:27], v[52:53], v[64:65]
	s_cbranch_vccnz .LBB0_285
	v_pk_mul_f32 v[30:31], v[30:31], s[28:29] op_sel_hi:[1,0]
	v_pk_mul_f32 v[28:29], v[28:29], s[28:29] op_sel_hi:[1,0]
	v_pk_mul_f32 v[22:23], v[22:23], s[28:29] op_sel_hi:[1,0]
	v_pk_mul_f32 v[20:21], v[20:21], s[28:29] op_sel_hi:[1,0]
	v_pk_mul_f32 v[34:35], v[34:35], s[28:29] op_sel_hi:[1,0]
	v_pk_mul_f32 v[32:33], v[32:33], s[28:29] op_sel_hi:[1,0]
	v_pk_mul_f32 v[26:27], v[26:27], s[28:29] op_sel_hi:[1,0]
	v_pk_mul_f32 v[24:25], v[24:25], s[28:29] op_sel_hi:[1,0]
	s_mov_b64 s[40:41], 0x19300000

; __device__ __forceinline__ u32x4 pack8(const f32x4 a, const f32x4 b) { u32x4 w; w.x = cvt_pk_bf16(a[0], a[1]); w.y = cvt_pk_bf16(a[2], a[3]); w.z = cvt_pk_bf16(b[0], b[1]); w.w = cvt_pk_bf16(b[2], b[3]); return w; }
; __device__ __forceinline__ void rope8(const float* tab64, int row, int fq, const f32x4 x1a, const f32x4 x2a, const f32x4 x1b, const f32x4 x2b, f32x4& a1, f32x4& a2, f32x4& b1, f32x4& b2) {
;     const float* tp = tab64 + ((size_t)pos_index_(row) * 32 + 8 * fq) * 2;
;     const f32x4 c0 = *(const f32x4*)tp, c1 = *(const f32x4*)(tp + 4), c2 = *(const f32x4*)(tp + 8), c3 = *(const f32x4*)(tp + 12);
;     rope4(x1a, x2a, c0, c1, a1, a2); rope4(x1b, x2b, c2, c3, b1, b2);
;     __device__ __forceinline__ void operator()(const f32x4 (&acc)[2][2][4][2], const Unit& u, int wr, int wc, int fr, int fq) const {
;     ...
;             for (int m = 0; m < 4; ++m) {
;                 const int rowb = u.pm * BM + ai * HALF + wr * 64 + m * 16, row0 = rowb + (fr & 7); const size_t ro0 = (size_t)row0 * 2048;
;                 float* f0 = row0 < 8192 ? (type == 1 ? okp : ovp) + ro0 : (type == 1 ? oks : ovs) + (ro0 - (size_t)8192 * 2048);
;                 if (type < 2) {
;                     f32x4 a1, a2, b1, b2; rope8(tab64, rowb + fr, fq, acc[ai][0][m][0], acc[ai][1][m][0], acc[ai][0][m][1], acc[ai][1][m][1], a1, a2, b1, b2);
;                     if (type == 0) { a1 = a1 * qscale; a2 = a2 * qscale; b1 = b1 * qscale; b2 = b2 * qscale; }
;                     st2_bf16((type == 0 ? QA : KA) + ro0 + cw + (lo ? 0 : 32), 8 * 2048, pack8(a1, b1), pack8(a2, b2), lo, dry);
;                     if (type == 1) { st2_f32<true>(f0 + cw + (lo ? 0 : 4), 8 * 2048, a1, b1, lo, dry); st2_f32<true>(f0 + cw + 32 + (lo ? 0 : 4), 8 * 2048, a2, b2, lo, dry); }
.Lrope_j_p1_7:
	v_mov_b64_e32 v[24:25], v[236:237]
	v_mov_b64_e32 v[26:27], v[238:239]
	v_mov_b64_e32 v[28:29], v[240:241]
	v_mov_b64_e32 v[30:31], v[242:243]
	v_mov_b64_e32 v[32:33], v[244:245]
	v_mov_b64_e32 v[34:35], v[246:247]
	v_mov_b64_e32 v[36:37], v[248:249]
	v_mov_b64_e32 v[38:39], v[250:251]
	s_and_b64 vcc, exec, s[6:7]
	s_mov_b64 s[6:7], 0x1b500000
	v_mov_b32_e32 v18, v24
	v_mul_f32_e32 v24, v16, v28
	v_mul_f32_e32 v40, v8, v29
	v_mul_f32_e32 v28, v8, v28
	v_mul_f32_e32 v42, v16, v29
	v_mov_b32_e32 v8, v17
	v_mov_b32_e32 v16, v9
	v_mov_b32_e32 v44, v32
	v_mul_f32_e32 v32, v12, v36
	v_mul_f32_e32 v46, v4, v37
	v_mul_f32_e32 v36, v4, v36
	v_mul_f32_e32 v48, v12, v37
	v_mov_b32_e32 v4, v13
	v_mov_b32_e32 v12, v5
	v_mov_b32_e32 v19, v26
	v_mov_b32_e32 v26, v25
	v_mov_b32_e32 v45, v34
	v_mov_b32_e32 v34, v33
	v_pk_mul_f32 v[8:9], v[8:9], v[30:31]
	v_pk_mul_f32 v[16:17], v[16:17], v[30:31]
	v_pk_mul_f32 v[52:53], v[4:5], v[38:39]
	v_pk_mul_f32 v[38:39], v[12:13], v[38:39]
	v_pk_mul_f32 v[50:51], v[6:7], v[26:27]
	v_pk_mul_f32 v[26:27], v[14:15], v[26:27]
	v_pk_mul_f32 v[30:31], v[2:3], v[34:35]
	v_pk_mul_f32 v[34:35], v[10:11], v[34:35]
	v_mov_b32_e32 v25, v8
	v_mov_b32_e32 v41, v9
	v_mov_b32_e32 v29, v16
	v_mov_b32_e32 v43, v17
	v_mov_b32_e32 v33, v52
	v_mov_b32_e32 v47, v53
	v_mov_b32_e32 v37, v38
	v_mov_b32_e32 v49, v39
	v_pk_fma_f32 v[12:13], v[14:15], v[18:19], v[50:51] neg_lo:[0,0,1] neg_hi:[0,0,1]
	v_pk_fma_f32 v[4:5], v[6:7], v[18:19], v[26:27]
	v_pk_fma_f32 v[16:17], v[10:11], v[44:45], v[30:31] neg_lo:[0,0,1] neg_hi:[0,0,1]
	v_pk_fma_f32 v[8:9], v[2:3], v[44:45], v[34:35]
	v_pk_add_f32 v[14:15], v[24:25], v[40:41] neg_lo:[0,1] neg_hi:[0,1]
	v_pk_add_f32 v[6:7], v[28:29], v[42:43]
	v_pk_add_f32 v[18:19], v[32:33], v[46:47] neg_lo:[0,1] neg_hi:[0,1]
	v_pk_add_f32 v[10:11], v[36:37], v[48:49]
	s_cbranch_vccnz .LBB0_300
	v_pk_mul_f32 v[14:15], v[14:15], s[28:29] op_sel_hi:[1,0]
	v_pk_mul_f32 v[12:13], v[12:13], s[28:29] op_sel_hi:[1,0]
	v_pk_mul_f32 v[6:7], v[6:7], s[28:29] op_sel_hi:[1,0]
	v_pk_mul_f32 v[4:5], v[4:5], s[28:29] op_sel_hi:[1,0]
	v_pk_mul_f32 v[18:19], v[18:19], s[28:29] op_sel_hi:[1,0]
	v_pk_mul_f32 v[16:17], v[16:17], s[28:29] op_sel_hi:[1,0]
	v_pk_mul_f32 v[10:11], v[10:11], s[28:29] op_sel_hi:[1,0]
	v_pk_mul_f32 v[8:9], v[8:9], s[28:29] op_sel_hi:[1,0]
	s_mov_b64 s[6:7], 0x19300000
